# merged MFMA priority windows + K-loop LDS-DMA in SGPR-base form (no loader VALU address adds) in up-proj and in-proj loops
# baseline (speedup 1.0000x reference)
; #define PG8_STAGE(bufoff, gbase, voff) do { _Pragma("unroll") for (int _i = 0; _i < 2; ++_i) \
;         __builtin_amdgcn_global_load_lds((const unsigned*)((const char*)(gbase) + (voff)[_i]), (PG8_LAS unsigned*)(lds + (bufoff) + ldsw + _i * 8192), 16, 0, 0); } while (0)
; #define PG8_LDA(dst, b, h) do { _Pragma("unroll") for (int m = 0; m < 4; ++m) _Pragma("unroll") for (int k = 0; k < 2; ++k) dst[m][k] = *(const PG8_LAS bf16x8*)(lds + PG8_SA(b, h) + aoff + m * 2048 + k * 1024); } while (0)
; #define PG8_LDB(dst, b, h) do { _Pragma("unroll") for (int n = 0; n < 2; ++n) _Pragma("unroll") for (int k = 0; k < 2; ++k) dst[n][k] = *(const PG8_LAS bf16x8*)(lds + PG8_SB(b, h) + boff + n * 2048 + k * 1024); } while (0)
; #define PG8_MMA(ai, bj, At, Bt) do { __builtin_amdgcn_s_setprio(1); _Pragma("unroll") for (int m = 0; m < 4; ++m) _Pragma("unroll") for (int n = 0; n < 2; ++n) _Pragma("unroll") for (int k = 0; k < 2; ++k) \
;         acc[ai][bj][m][n] = __builtin_amdgcn_mfma_f32_16x16x32_bf16(Bt[n][k], At[m][k], acc[ai][bj][m][n], 0, 0, 0); __builtin_amdgcn_s_setprio(0); } while (0)
; #define PG8_WAIT_V(n) asm volatile("s_waitcnt vmcnt(" #n ")" ::: "memory")
; #define PG8_BAR __builtin_amdgcn_s_barrier()
; template <class Epi, class Sched, bool ALIGN_EPI = false, bool SP2 = false>
; __device__ __forceinline__ void gemm_phase(PG8_LAS unsigned char* lds, const Gemm g, const Sched& S, const Epi& E, int tid_in) {
;     ...
;         for (int t = 0; t < nt; t += 2) {
;             const bool last = (t == nt - 2);
;             const char* a1 = cA + (size_t)(t + 1) * kstep;
;             const char* a2 = last ? nA : cA + (size_t)(t + 2) * kstep; const char* b2 = last ? nB : cB + (size_t)(t + 2) * kstep;
;             const char* a3 = a2 + kstep; const char* b3 = b2 + kstep;
;             if (last && has_next) S.a_ready(nxt);
;             if constexpr (SP2) {
;             PG8_LDB(B0, 0, 0); PG8_LDB(B1, 0, 1); PG8_SCHED; PG8_LDA(At, 0, 0); PG8_STAGE(PG8_SA(1, 1), a1 + hstep, voffA);
;             PG8_WAIT_V(8); PG8_WAIT_L(0); PG8_BAR; PG8_MMA(0, 0, At, B0); PG8_MMA(0, 1, At, B1); PG8_BAR; PG8_SCHED;
;             PG8_LDA(At, 0, 1); PG8_STAGE(PG8_SB(0, 0), b2, voffB); PG8_STAGE(PG8_SB(0, 1), b2 + hstep, voffB); PG8_STAGE(PG8_SA(0, 0), a2, voffA);
;             PG8_WAIT_V(8); PG8_WAIT_L(0); PG8_BAR; PG8_MMA(1, 0, At, B0); PG8_MMA(1, 1, At, B1); PG8_BAR; PG8_SCHED;
.LBB0_219:
	s_add_u32 s0, s24, 0xfffc0080
	s_addc_u32 s1, s25, -1
	s_add_i32 s2, 0, 0x10000
	s_cmp_eq_u32 s55, 12
	s_cselect_b32 s29, s7, s1
	s_cselect_b32 s28, s9, s0
	s_cselect_b32 s27, s17, s54
	s_cselect_b32 s26, s19, s53
	s_add_i32 s3, 0, 0x14000
	v_add_u32_e32 v140, s2, v168
	v_add_u32_e32 v174, s3, v168
	ds_read_b128 v[128:131], v140
	ds_read_b128 v[132:135], v140 offset:1024
	ds_read_b128 v[136:139], v140 offset:2048
	ds_read_b128 v[140:143], v140 offset:3072
	ds_read_b128 v[158:161], v174
	ds_read_b128 v[162:165], v174 offset:1024
	ds_read_b128 v[170:173], v174 offset:2048
	ds_read_b128 v[174:177], v174 offset:3072
	s_add_i32 m0, s41, 0xc000
	ds_read_b128 v[178:181], v169
	ds_read_b128 v[182:185], v169 offset:1024
	ds_read_b128 v[186:189], v169 offset:2048
	ds_read_b128 v[190:193], v169 offset:3072
	ds_read_b128 v[194:197], v169 offset:4096
	ds_read_b128 v[198:201], v169 offset:5120
	ds_read_b128 v[202:205], v169 offset:6144
	ds_read_b128 v[206:209], v169 offset:7168
	global_load_lds_dwordx4 v154, s[24:25]
	s_add_i32 m0, s41, 0xe000
	s_nop 0
	global_load_lds_dwordx4 v156, s[24:25]
	s_waitcnt vmcnt(8)
	s_waitcnt lgkmcnt(0)
	s_barrier
	s_setprio 1
	s_waitcnt lgkmcnt(0)
	v_mfma_f32_16x16x32_bf16 v[124:127], v[128:131], v[178:181], v[124:127]
	v_mfma_f32_16x16x32_bf16 v[120:123], v[136:139], v[178:181], v[120:123]
	v_mfma_f32_16x16x32_bf16 v[108:111], v[128:131], v[186:189], v[108:111]
	v_mfma_f32_16x16x32_bf16 v[104:107], v[136:139], v[186:189], v[104:107]
	v_mfma_f32_16x16x32_bf16 v[92:95], v[128:131], v[194:197], v[92:95]
	v_mfma_f32_16x16x32_bf16 v[88:91], v[136:139], v[194:197], v[88:91]
	v_mfma_f32_16x16x32_bf16 v[76:79], v[128:131], v[202:205], v[76:79]
	v_mfma_f32_16x16x32_bf16 v[72:75], v[136:139], v[202:205], v[72:75]
	v_mfma_f32_16x16x32_bf16 v[124:127], v[132:135], v[182:185], v[124:127]
	v_mfma_f32_16x16x32_bf16 v[120:123], v[140:143], v[182:185], v[120:123]
	v_mfma_f32_16x16x32_bf16 v[108:111], v[132:135], v[190:193], v[108:111]
	v_mfma_f32_16x16x32_bf16 v[104:107], v[140:143], v[190:193], v[104:107]
	v_mfma_f32_16x16x32_bf16 v[92:95], v[132:135], v[198:201], v[92:95]
	v_mfma_f32_16x16x32_bf16 v[88:91], v[140:143], v[198:201], v[88:91]
	v_mfma_f32_16x16x32_bf16 v[76:79], v[132:135], v[206:209], v[76:79]
	v_mfma_f32_16x16x32_bf16 v[72:75], v[140:143], v[206:209], v[72:75]
	v_mfma_f32_16x16x32_bf16 v[116:119], v[158:161], v[178:181], v[116:119]
	v_mfma_f32_16x16x32_bf16 v[112:115], v[170:173], v[178:181], v[112:115]
	v_mfma_f32_16x16x32_bf16 v[100:103], v[158:161], v[186:189], v[100:103]
	v_mfma_f32_16x16x32_bf16 v[96:99], v[170:173], v[186:189], v[96:99]
	v_mfma_f32_16x16x32_bf16 v[84:87], v[158:161], v[194:197], v[84:87]
	v_mfma_f32_16x16x32_bf16 v[80:83], v[170:173], v[194:197], v[80:83]
	v_mfma_f32_16x16x32_bf16 v[68:71], v[158:161], v[202:205], v[68:71]
	v_mfma_f32_16x16x32_bf16 v[64:67], v[170:173], v[202:205], v[64:67]
	v_mfma_f32_16x16x32_bf16 v[116:119], v[162:165], v[182:185], v[116:119]
	v_mfma_f32_16x16x32_bf16 v[112:115], v[174:177], v[182:185], v[112:115]
	v_mfma_f32_16x16x32_bf16 v[100:103], v[162:165], v[190:193], v[100:103]
	v_mfma_f32_16x16x32_bf16 v[96:99], v[174:177], v[190:193], v[96:99]
	v_mfma_f32_16x16x32_bf16 v[84:87], v[162:165], v[198:201], v[84:87]
	v_mfma_f32_16x16x32_bf16 v[80:83], v[174:177], v[198:201], v[80:83]
	v_mfma_f32_16x16x32_bf16 v[68:71], v[162:165], v[206:209], v[68:71]
	v_mfma_f32_16x16x32_bf16 v[64:67], v[174:177], v[206:209], v[64:67]
	s_setprio 0
	s_barrier
	s_add_i32 s0, s2, s40
	s_mov_b32 m0, s0
	ds_read_b128 v[178:181], v169 offset:16384
	ds_read_b128 v[182:185], v169 offset:17408
	ds_read_b128 v[186:189], v169 offset:18432
	ds_read_b128 v[190:193], v169 offset:19456
	ds_read_b128 v[194:197], v169 offset:20480
	ds_read_b128 v[198:201], v169 offset:21504
	ds_read_b128 v[202:205], v169 offset:22528
	ds_read_b128 v[206:209], v169 offset:23552
	global_load_lds_dwordx4 v144, s[26:27]
	s_add_i32 m0, s0, 0x2000
	s_add_u32 s0, s26, 0x40000
	s_addc_u32 s1, s27, 0
	s_add_i32 s2, s3, s40
	global_load_lds_dwordx4 v152, s[26:27]
	s_mov_b32 m0, s2
	s_nop 0
	global_load_lds_dwordx4 v144, s[0:1]
	s_add_i32 m0, s2, 0x2000
	s_nop 0
	global_load_lds_dwordx4 v152, s[0:1]
	s_mov_b32 m0, s41
	s_nop 0
	global_load_lds_dwordx4 v148, s[28:29]
	s_mov_b32 m0, s42
	s_nop 0
	global_load_lds_dwordx4 v150, s[28:29]
	s_waitcnt vmcnt(8)
	s_waitcnt lgkmcnt(0)
	s_barrier
	s_setprio 1
	s_waitcnt lgkmcnt(0)
	v_mfma_f32_16x16x32_bf16 v[60:63], v[128:131], v[178:181], v[60:63]
	v_mfma_f32_16x16x32_bf16 v[56:59], v[136:139], v[178:181], v[56:59]
	v_mfma_f32_16x16x32_bf16 v[44:47], v[128:131], v[186:189], v[44:47]
	v_mfma_f32_16x16x32_bf16 v[40:43], v[136:139], v[186:189], v[40:43]
	v_mfma_f32_16x16x32_bf16 v[28:31], v[128:131], v[194:197], v[28:31]
	v_mfma_f32_16x16x32_bf16 v[24:27], v[136:139], v[194:197], v[24:27]
	v_mfma_f32_16x16x32_bf16 v[12:15], v[128:131], v[202:205], v[12:15]
	v_mfma_f32_16x16x32_bf16 v[8:11], v[136:139], v[202:205], v[8:11]
	v_mfma_f32_16x16x32_bf16 v[60:63], v[132:135], v[182:185], v[60:63]
	v_mfma_f32_16x16x32_bf16 v[56:59], v[140:143], v[182:185], v[56:59]
	v_mfma_f32_16x16x32_bf16 v[44:47], v[132:135], v[190:193], v[44:47]
	v_mfma_f32_16x16x32_bf16 v[40:43], v[140:143], v[190:193], v[40:43]
	v_mfma_f32_16x16x32_bf16 v[28:31], v[132:135], v[198:201], v[28:31]
	v_mfma_f32_16x16x32_bf16 v[24:27], v[140:143], v[198:201], v[24:27]
	v_mfma_f32_16x16x32_bf16 v[12:15], v[132:135], v[206:209], v[12:15]
	v_mfma_f32_16x16x32_bf16 v[8:11], v[140:143], v[206:209], v[8:11]
	v_mfma_f32_16x16x32_bf16 v[52:55], v[158:161], v[178:181], v[52:55]
	v_mfma_f32_16x16x32_bf16 v[48:51], v[170:173], v[178:181], v[48:51]
	v_mfma_f32_16x16x32_bf16 v[36:39], v[158:161], v[186:189], v[36:39]
	v_mfma_f32_16x16x32_bf16 v[32:35], v[170:173], v[186:189], v[32:35]
	v_mfma_f32_16x16x32_bf16 v[20:23], v[158:161], v[194:197], v[20:23]
	v_mfma_f32_16x16x32_bf16 v[16:19], v[170:173], v[194:197], v[16:19]
	v_mfma_f32_16x16x32_bf16 v[4:7], v[158:161], v[202:205], v[4:7]
	v_mfma_f32_16x16x32_bf16 v[0:3], v[170:173], v[202:205], v[0:3]
	v_mfma_f32_16x16x32_bf16 v[52:55], v[162:165], v[182:185], v[52:55]
	v_mfma_f32_16x16x32_bf16 v[48:51], v[174:177], v[182:185], v[48:51]
	v_mfma_f32_16x16x32_bf16 v[36:39], v[162:165], v[190:193], v[36:39]
	v_mfma_f32_16x16x32_bf16 v[32:35], v[174:177], v[190:193], v[32:35]
	v_mfma_f32_16x16x32_bf16 v[20:23], v[162:165], v[198:201], v[20:23]
	v_mfma_f32_16x16x32_bf16 v[16:19], v[174:177], v[198:201], v[16:19]
	v_mfma_f32_16x16x32_bf16 v[4:7], v[162:165], v[206:209], v[4:7]
	v_mfma_f32_16x16x32_bf16 v[0:3], v[174:177], v[206:209], v[0:3]
	s_setprio 0
	s_barrier
; #define PG8_STAGE(bufoff, gbase, voff) do { _Pragma("unroll") for (int _i = 0; _i < 2; ++_i) \
;         __builtin_amdgcn_global_load_lds((const unsigned*)((const char*)(gbase) + (voff)[_i]), (PG8_LAS unsigned*)(lds + (bufoff) + ldsw + _i * 8192), 16, 0, 0); } while (0)
; #define PG8_LDA(dst, b, h) do { _Pragma("unroll") for (int m = 0; m < 4; ++m) _Pragma("unroll") for (int k = 0; k < 2; ++k) dst[m][k] = *(const PG8_LAS bf16x8*)(lds + PG8_SA(b, h) + aoff + m * 2048 + k * 1024); } while (0)
; #define PG8_LDB(dst, b, h) do { _Pragma("unroll") for (int n = 0; n < 2; ++n) _Pragma("unroll") for (int k = 0; k < 2; ++k) dst[n][k] = *(const PG8_LAS bf16x8*)(lds + PG8_SB(b, h) + boff + n * 2048 + k * 1024); } while (0)
; #define PG8_MMA(ai, bj, At, Bt) do { __builtin_amdgcn_s_setprio(1); _Pragma("unroll") for (int m = 0; m < 4; ++m) _Pragma("unroll") for (int n = 0; n < 2; ++n) _Pragma("unroll") for (int k = 0; k < 2; ++k) \
;         acc[ai][bj][m][n] = __builtin_amdgcn_mfma_f32_16x16x32_bf16(Bt[n][k], At[m][k], acc[ai][bj][m][n], 0, 0, 0); __builtin_amdgcn_s_setprio(0); } while (0)
; #define PG8_WAIT_V(n) asm volatile("s_waitcnt vmcnt(" #n ")" ::: "memory")
; #define PG8_WAIT_L(n) asm volatile("s_waitcnt lgkmcnt(" #n ")" ::: "memory")
; #define PG8_BAR __builtin_amdgcn_s_barrier()
; #define PG8_SCHED __builtin_amdgcn_sched_barrier(0)
; template <class Epi, class Sched, bool ALIGN_EPI = false, bool SP2 = false>
; __device__ __forceinline__ void gemm_phase(PG8_LAS unsigned char* lds, const Gemm g, const Sched& S, const Epi& E, int tid_in) {
;     ...
;             PG8_LDB(B0, 1, 0); PG8_LDB(B1, 1, 1); PG8_SCHED; PG8_LDA(At, 1, 0); PG8_STAGE(PG8_SA(0, 1), a2 + hstep, voffA);
;             PG8_WAIT_V(8); PG8_WAIT_L(0); PG8_BAR; PG8_MMA(0, 0, At, B0); PG8_MMA(0, 1, At, B1); PG8_BAR; PG8_SCHED;
;             PG8_LDA(At, 1, 1); PG8_STAGE(PG8_SB(1, 0), b3, voffB); PG8_STAGE(PG8_SB(1, 1), b3 + hstep, voffB); PG8_STAGE(PG8_SA(1, 0), a3, voffA);
;             PG8_WAIT_V(8); PG8_WAIT_L(0); PG8_BAR; PG8_MMA(1, 0, At, B0); PG8_MMA(1, 1, At, B1); PG8_BAR; PG8_SCHED;
	s_add_i32 s2, 0, 0x18000
	s_add_i32 s3, 0, 0x1c000
	v_add_u32_e32 v140, s2, v168
	v_add_u32_e32 v174, s3, v168
	ds_read_b128 v[128:131], v140
	ds_read_b128 v[132:135], v140 offset:1024
	ds_read_b128 v[136:139], v140 offset:2048
	ds_read_b128 v[140:143], v140 offset:3072
	ds_read_b128 v[158:161], v174
	ds_read_b128 v[162:165], v174 offset:1024
	ds_read_b128 v[170:173], v174 offset:2048
	ds_read_b128 v[174:177], v174 offset:3072
	s_add_u32 s0, s28, 0x40000
	s_addc_u32 s1, s29, 0
	s_mov_b32 m0, s43
	ds_read_b128 v[178:181], v169 offset:32768
	ds_read_b128 v[182:185], v169 offset:33792
	ds_read_b128 v[186:189], v169 offset:34816
	ds_read_b128 v[190:193], v169 offset:35840
	ds_read_b128 v[194:197], v169 offset:36864
	ds_read_b128 v[198:201], v169 offset:37888
	ds_read_b128 v[202:205], v169 offset:38912
	ds_read_b128 v[206:209], v169 offset:39936
	global_load_lds_dwordx4 v148, s[0:1]
	s_mov_b32 m0, s44
	s_nop 0
	global_load_lds_dwordx4 v150, s[0:1]
	s_waitcnt vmcnt(8)
	s_waitcnt lgkmcnt(0)
	s_barrier
	s_setprio 1
	s_waitcnt lgkmcnt(0)
	v_mfma_f32_16x16x32_bf16 v[124:127], v[128:131], v[178:181], v[124:127]
	v_mfma_f32_16x16x32_bf16 v[120:123], v[136:139], v[178:181], v[120:123]
	v_mfma_f32_16x16x32_bf16 v[108:111], v[128:131], v[186:189], v[108:111]
	v_mfma_f32_16x16x32_bf16 v[104:107], v[136:139], v[186:189], v[104:107]
	v_mfma_f32_16x16x32_bf16 v[92:95], v[128:131], v[194:197], v[92:95]
	v_mfma_f32_16x16x32_bf16 v[88:91], v[136:139], v[194:197], v[88:91]
	v_mfma_f32_16x16x32_bf16 v[76:79], v[128:131], v[202:205], v[76:79]
	v_mfma_f32_16x16x32_bf16 v[72:75], v[136:139], v[202:205], v[72:75]
	v_mfma_f32_16x16x32_bf16 v[124:127], v[132:135], v[182:185], v[124:127]
	v_mfma_f32_16x16x32_bf16 v[120:123], v[140:143], v[182:185], v[120:123]
	v_mfma_f32_16x16x32_bf16 v[108:111], v[132:135], v[190:193], v[108:111]
	v_mfma_f32_16x16x32_bf16 v[104:107], v[140:143], v[190:193], v[104:107]
	v_mfma_f32_16x16x32_bf16 v[92:95], v[132:135], v[198:201], v[92:95]
	v_mfma_f32_16x16x32_bf16 v[88:91], v[140:143], v[198:201], v[88:91]
	v_mfma_f32_16x16x32_bf16 v[76:79], v[132:135], v[206:209], v[76:79]
	v_mfma_f32_16x16x32_bf16 v[72:75], v[140:143], v[206:209], v[72:75]
	v_mfma_f32_16x16x32_bf16 v[116:119], v[158:161], v[178:181], v[116:119]
	v_mfma_f32_16x16x32_bf16 v[112:115], v[170:173], v[178:181], v[112:115]
	v_mfma_f32_16x16x32_bf16 v[100:103], v[158:161], v[186:189], v[100:103]
	v_mfma_f32_16x16x32_bf16 v[96:99], v[170:173], v[186:189], v[96:99]
	v_mfma_f32_16x16x32_bf16 v[84:87], v[158:161], v[194:197], v[84:87]
	v_mfma_f32_16x16x32_bf16 v[80:83], v[170:173], v[194:197], v[80:83]
	v_mfma_f32_16x16x32_bf16 v[68:71], v[158:161], v[202:205], v[68:71]
	v_mfma_f32_16x16x32_bf16 v[64:67], v[170:173], v[202:205], v[64:67]
	v_mfma_f32_16x16x32_bf16 v[116:119], v[162:165], v[182:185], v[116:119]
	v_mfma_f32_16x16x32_bf16 v[112:115], v[174:177], v[182:185], v[112:115]
	v_mfma_f32_16x16x32_bf16 v[100:103], v[162:165], v[190:193], v[100:103]
	v_mfma_f32_16x16x32_bf16 v[96:99], v[174:177], v[190:193], v[96:99]
	v_mfma_f32_16x16x32_bf16 v[84:87], v[162:165], v[198:201], v[84:87]
	v_mfma_f32_16x16x32_bf16 v[80:83], v[174:177], v[198:201], v[80:83]
	v_mfma_f32_16x16x32_bf16 v[68:71], v[162:165], v[206:209], v[68:71]
	v_mfma_f32_16x16x32_bf16 v[64:67], v[174:177], v[206:209], v[64:67]
	s_setprio 0
	s_barrier
	s_add_i32 s0, s2, s40
	s_add_u32 s98, s26, 0x80
	s_addc_u32 s99, s27, 0
	s_mov_b32 m0, s0
	ds_read_b128 v[178:181], v169 offset:49152
	ds_read_b128 v[182:185], v169 offset:50176
	ds_read_b128 v[186:189], v169 offset:51200
	ds_read_b128 v[190:193], v169 offset:52224
	ds_read_b128 v[194:197], v169 offset:53248
	ds_read_b128 v[198:201], v169 offset:54272
	ds_read_b128 v[202:205], v169 offset:55296
	ds_read_b128 v[206:209], v169 offset:56320
	global_load_lds_dwordx4 v144, s[98:99]
	s_add_i32 m0, s0, 0x2000
	s_add_u32 s0, s26, 0x40080
	s_addc_u32 s1, s27, 0
	s_add_i32 s2, s3, s40
	global_load_lds_dwordx4 v152, s[98:99]
	s_mov_b32 m0, s2
	s_nop 0
	global_load_lds_dwordx4 v144, s[0:1]
	s_add_i32 m0, s2, 0x2000
	s_nop 0
	global_load_lds_dwordx4 v152, s[0:1]
	s_add_u32 s98, s28, 0x80
	s_addc_u32 s99, s29, 0
	s_mov_b32 m0, s50
	s_nop 0
	global_load_lds_dwordx4 v148, s[98:99]
	s_mov_b32 m0, s51
	s_nop 0
	global_load_lds_dwordx4 v150, s[98:99]
	s_waitcnt vmcnt(8)
	s_waitcnt lgkmcnt(0)
	s_barrier
	s_setprio 1
	s_waitcnt lgkmcnt(0)
	v_mfma_f32_16x16x32_bf16 v[60:63], v[128:131], v[178:181], v[60:63]
	v_mfma_f32_16x16x32_bf16 v[56:59], v[136:139], v[178:181], v[56:59]
	v_mfma_f32_16x16x32_bf16 v[44:47], v[128:131], v[186:189], v[44:47]
	v_mfma_f32_16x16x32_bf16 v[40:43], v[136:139], v[186:189], v[40:43]
	v_mfma_f32_16x16x32_bf16 v[28:31], v[128:131], v[194:197], v[28:31]
	v_mfma_f32_16x16x32_bf16 v[24:27], v[136:139], v[194:197], v[24:27]
	v_mfma_f32_16x16x32_bf16 v[12:15], v[128:131], v[202:205], v[12:15]
	v_mfma_f32_16x16x32_bf16 v[8:11], v[136:139], v[202:205], v[8:11]
	v_mfma_f32_16x16x32_bf16 v[60:63], v[132:135], v[182:185], v[60:63]
	v_mfma_f32_16x16x32_bf16 v[56:59], v[140:143], v[182:185], v[56:59]
	v_mfma_f32_16x16x32_bf16 v[44:47], v[132:135], v[190:193], v[44:47]
	v_mfma_f32_16x16x32_bf16 v[40:43], v[140:143], v[190:193], v[40:43]
	v_mfma_f32_16x16x32_bf16 v[28:31], v[132:135], v[198:201], v[28:31]
	v_mfma_f32_16x16x32_bf16 v[24:27], v[140:143], v[198:201], v[24:27]
	v_mfma_f32_16x16x32_bf16 v[12:15], v[132:135], v[206:209], v[12:15]
	v_mfma_f32_16x16x32_bf16 v[8:11], v[140:143], v[206:209], v[8:11]
	v_mfma_f32_16x16x32_bf16 v[52:55], v[158:161], v[178:181], v[52:55]
	v_mfma_f32_16x16x32_bf16 v[48:51], v[170:173], v[178:181], v[48:51]
	v_mfma_f32_16x16x32_bf16 v[36:39], v[158:161], v[186:189], v[36:39]
	v_mfma_f32_16x16x32_bf16 v[32:35], v[170:173], v[186:189], v[32:35]
	v_mfma_f32_16x16x32_bf16 v[20:23], v[158:161], v[194:197], v[20:23]
	v_mfma_f32_16x16x32_bf16 v[16:19], v[170:173], v[194:197], v[16:19]
	v_mfma_f32_16x16x32_bf16 v[4:7], v[158:161], v[202:205], v[4:7]
	v_mfma_f32_16x16x32_bf16 v[0:3], v[170:173], v[202:205], v[0:3]
	v_mfma_f32_16x16x32_bf16 v[52:55], v[162:165], v[182:185], v[52:55]
	v_mfma_f32_16x16x32_bf16 v[48:51], v[174:177], v[182:185], v[48:51]
	v_mfma_f32_16x16x32_bf16 v[36:39], v[162:165], v[190:193], v[36:39]
	v_mfma_f32_16x16x32_bf16 v[32:35], v[174:177], v[190:193], v[32:35]
	v_mfma_f32_16x16x32_bf16 v[20:23], v[162:165], v[198:201], v[20:23]
	v_mfma_f32_16x16x32_bf16 v[16:19], v[174:177], v[198:201], v[16:19]
	v_mfma_f32_16x16x32_bf16 v[4:7], v[162:165], v[206:209], v[4:7]
	v_mfma_f32_16x16x32_bf16 v[0:3], v[174:177], v[206:209], v[0:3]
	s_setprio 0
	s_barrier
	s_add_i32 s55, s55, 2
	s_add_u32 s24, s24, 0x100
	s_addc_u32 s25, s25, 0
	s_add_u32 s53, s53, 0x100
	s_addc_u32 s54, s54, 0
	s_cmp_gt_u32 s55, 13
	s_cbranch_scc0 .LBB0_219
	s_and_b64 vcc, exec, s[14:15]
	s_cbranch_vccz .LBB0_222
	s_barrier

; #define PG8_STAGE(bufoff, gbase, voff) do { _Pragma("unroll") for (int _i = 0; _i < 2; ++_i) \
;         __builtin_amdgcn_global_load_lds((const unsigned*)((const char*)(gbase) + (voff)[_i]), (PG8_LAS unsigned*)(lds + (bufoff) + ldsw + _i * 8192), 16, 0, 0); } while (0)
; #define PG8_LDA(dst, b, h) do { _Pragma("unroll") for (int m = 0; m < 4; ++m) _Pragma("unroll") for (int k = 0; k < 2; ++k) dst[m][k] = *(const PG8_LAS bf16x8*)(lds + PG8_SA(b, h) + aoff + m * 2048 + k * 1024); } while (0)
; #define PG8_LDB(dst, b, h) do { _Pragma("unroll") for (int n = 0; n < 2; ++n) _Pragma("unroll") for (int k = 0; k < 2; ++k) dst[n][k] = *(const PG8_LAS bf16x8*)(lds + PG8_SB(b, h) + boff + n * 2048 + k * 1024); } while (0)
; #define PG8_MMA(ai, bj, At, Bt) do { __builtin_amdgcn_s_setprio(1); _Pragma("unroll") for (int m = 0; m < 4; ++m) _Pragma("unroll") for (int n = 0; n < 2; ++n) _Pragma("unroll") for (int k = 0; k < 2; ++k) \
;         acc[ai][bj][m][n] = __builtin_amdgcn_mfma_f32_16x16x32_bf16(Bt[n][k], At[m][k], acc[ai][bj][m][n], 0, 0, 0); __builtin_amdgcn_s_setprio(0); } while (0)
; #define PG8_WAIT_V(n) asm volatile("s_waitcnt vmcnt(" #n ")" ::: "memory")
; #define PG8_BAR __builtin_amdgcn_s_barrier()
; template <class Epi, class Sched, bool ALIGN_EPI = false, bool SP2 = false>
; __device__ __forceinline__ void gemm_phase(PG8_LAS unsigned char* lds, const Gemm g, const Sched& S, const Epi& E, int tid_in) {
;     ...
;         for (int t = 0; t < nt; t += 2) {
;             const bool last = (t == nt - 2);
;             const char* a1 = cA + (size_t)(t + 1) * kstep;
;             const char* a2 = last ? nA : cA + (size_t)(t + 2) * kstep; const char* b2 = last ? nB : cB + (size_t)(t + 2) * kstep;
;             const char* a3 = a2 + kstep; const char* b3 = b2 + kstep;
;             if (last && has_next) S.a_ready(nxt);
;             if constexpr (SP2) {
;             PG8_LDB(B0, 0, 0); PG8_LDB(B1, 0, 1); PG8_SCHED; PG8_LDA(At, 0, 0); PG8_STAGE(PG8_SA(1, 1), a1 + hstep, voffA);
;             PG8_WAIT_V(8); PG8_WAIT_L(0); PG8_BAR; PG8_MMA(0, 0, At, B0); PG8_MMA(0, 1, At, B1); PG8_BAR; PG8_SCHED;
;             PG8_LDA(At, 0, 1); PG8_STAGE(PG8_SB(0, 0), b2, voffB); PG8_STAGE(PG8_SB(0, 1), b2 + hstep, voffB); PG8_STAGE(PG8_SA(0, 0), a2, voffA);
;             PG8_WAIT_V(8); PG8_WAIT_L(0); PG8_BAR; PG8_MMA(1, 0, At, B0); PG8_MMA(1, 1, At, B1); PG8_BAR; PG8_SCHED;
.LBB0_351:
	s_add_u32 s2, s20, 0xfffc0080
	s_addc_u32 s3, s21, -1
	s_add_i32 s33, 0, 0x10000
	s_cmp_eq_u32 s49, 12
	s_cselect_b32 s25, s11, s3
	s_cselect_b32 s24, s44, s2
	s_cselect_b32 s23, s9, s48
	s_cselect_b32 s22, s45, s47
	s_add_i32 s34, 0, 0x14000
	v_add_u32_e32 v60, s33, v164
	v_add_u32_e32 v174, s34, v164
	ds_read_b128 v[48:51], v60
	ds_read_b128 v[52:55], v60 offset:1024
	ds_read_b128 v[56:59], v60 offset:2048
	ds_read_b128 v[60:63], v60 offset:3072
	ds_read_b128 v[158:161], v174
	ds_read_b128 v[166:169], v174 offset:1024
	ds_read_b128 v[170:173], v174 offset:2048
	ds_read_b128 v[174:177], v174 offset:3072
	s_add_i32 m0, s19, 0xc000
	ds_read_b128 v[178:181], v165
	ds_read_b128 v[182:185], v165 offset:1024
	ds_read_b128 v[186:189], v165 offset:2048
	ds_read_b128 v[190:193], v165 offset:3072
	ds_read_b128 v[194:197], v165 offset:4096
	ds_read_b128 v[198:201], v165 offset:5120
	ds_read_b128 v[202:205], v165 offset:6144
	ds_read_b128 v[206:209], v165 offset:7168
	global_load_lds_dwordx4 v154, s[20:21]
	s_add_i32 m0, s19, 0xe000
	s_nop 0
	global_load_lds_dwordx4 v156, s[20:21]
	s_waitcnt vmcnt(8)
	s_waitcnt lgkmcnt(0)
	s_barrier
	s_setprio 1
	s_waitcnt lgkmcnt(0)
	v_mfma_f32_16x16x32_bf16 v[140:143], v[48:51], v[178:181], v[140:143]
	v_mfma_f32_16x16x32_bf16 v[136:139], v[56:59], v[178:181], v[136:139]
	v_mfma_f32_16x16x32_bf16 v[124:127], v[48:51], v[186:189], v[124:127]
	v_mfma_f32_16x16x32_bf16 v[120:123], v[56:59], v[186:189], v[120:123]
	v_mfma_f32_16x16x32_bf16 v[108:111], v[48:51], v[194:197], v[108:111]
	v_mfma_f32_16x16x32_bf16 v[104:107], v[56:59], v[194:197], v[104:107]
	v_mfma_f32_16x16x32_bf16 v[92:95], v[48:51], v[202:205], v[92:95]
	v_mfma_f32_16x16x32_bf16 v[88:91], v[56:59], v[202:205], v[88:91]
	v_mfma_f32_16x16x32_bf16 v[140:143], v[52:55], v[182:185], v[140:143]
	v_mfma_f32_16x16x32_bf16 v[136:139], v[60:63], v[182:185], v[136:139]
	v_mfma_f32_16x16x32_bf16 v[124:127], v[52:55], v[190:193], v[124:127]
	v_mfma_f32_16x16x32_bf16 v[120:123], v[60:63], v[190:193], v[120:123]
	v_mfma_f32_16x16x32_bf16 v[108:111], v[52:55], v[198:201], v[108:111]
	v_mfma_f32_16x16x32_bf16 v[104:107], v[60:63], v[198:201], v[104:107]
	v_mfma_f32_16x16x32_bf16 v[92:95], v[52:55], v[206:209], v[92:95]
	v_mfma_f32_16x16x32_bf16 v[88:91], v[60:63], v[206:209], v[88:91]
	v_mfma_f32_16x16x32_bf16 v[132:135], v[158:161], v[178:181], v[132:135]
	v_mfma_f32_16x16x32_bf16 v[128:131], v[170:173], v[178:181], v[128:131]
	v_mfma_f32_16x16x32_bf16 v[116:119], v[158:161], v[186:189], v[116:119]
	v_mfma_f32_16x16x32_bf16 v[112:115], v[170:173], v[186:189], v[112:115]
	v_mfma_f32_16x16x32_bf16 v[100:103], v[158:161], v[194:197], v[100:103]
	v_mfma_f32_16x16x32_bf16 v[96:99], v[170:173], v[194:197], v[96:99]
	v_mfma_f32_16x16x32_bf16 v[84:87], v[158:161], v[202:205], v[84:87]
	v_mfma_f32_16x16x32_bf16 v[80:83], v[170:173], v[202:205], v[80:83]
	v_mfma_f32_16x16x32_bf16 v[132:135], v[166:169], v[182:185], v[132:135]
	v_mfma_f32_16x16x32_bf16 v[128:131], v[174:177], v[182:185], v[128:131]
	v_mfma_f32_16x16x32_bf16 v[116:119], v[166:169], v[190:193], v[116:119]
	v_mfma_f32_16x16x32_bf16 v[112:115], v[174:177], v[190:193], v[112:115]
	v_mfma_f32_16x16x32_bf16 v[100:103], v[166:169], v[198:201], v[100:103]
	v_mfma_f32_16x16x32_bf16 v[96:99], v[174:177], v[198:201], v[96:99]
	v_mfma_f32_16x16x32_bf16 v[84:87], v[166:169], v[206:209], v[84:87]
	v_mfma_f32_16x16x32_bf16 v[80:83], v[174:177], v[206:209], v[80:83]
	s_setprio 0
	s_barrier
	s_add_i32 s2, s33, s35
	s_mov_b32 m0, s2
	ds_read_b128 v[178:181], v165 offset:16384
	ds_read_b128 v[182:185], v165 offset:17408
	ds_read_b128 v[186:189], v165 offset:18432
	ds_read_b128 v[190:193], v165 offset:19456
	ds_read_b128 v[194:197], v165 offset:20480
	ds_read_b128 v[198:201], v165 offset:21504
	ds_read_b128 v[202:205], v165 offset:22528
	ds_read_b128 v[206:209], v165 offset:23552
	global_load_lds_dwordx4 v144, s[22:23]
	s_add_i32 m0, s2, 0x2000
	s_add_u32 s2, s22, 0x40000
	s_addc_u32 s3, s23, 0
	s_add_i32 s33, s34, s35
	global_load_lds_dwordx4 v148, s[22:23]
	s_mov_b32 m0, s33
	s_nop 0
	global_load_lds_dwordx4 v144, s[2:3]
	s_add_i32 m0, s33, 0x2000
	s_nop 0
	global_load_lds_dwordx4 v148, s[2:3]
	s_mov_b32 m0, s19
	s_nop 0
	global_load_lds_dwordx4 v152, s[24:25]
	s_mov_b32 m0, s36
	s_nop 0
	global_load_lds_dwordx4 v150, s[24:25]
	s_waitcnt vmcnt(8)
	s_waitcnt lgkmcnt(0)
	s_barrier
	s_setprio 1
	s_waitcnt lgkmcnt(0)
	v_mfma_f32_16x16x32_bf16 v[76:79], v[48:51], v[178:181], v[76:79]
	v_mfma_f32_16x16x32_bf16 v[72:75], v[56:59], v[178:181], v[72:75]
	v_mfma_f32_16x16x32_bf16 v[44:47], v[48:51], v[186:189], v[44:47]
	v_mfma_f32_16x16x32_bf16 v[40:43], v[56:59], v[186:189], v[40:43]
	v_mfma_f32_16x16x32_bf16 v[28:31], v[48:51], v[194:197], v[28:31]
	v_mfma_f32_16x16x32_bf16 v[24:27], v[56:59], v[194:197], v[24:27]
	v_mfma_f32_16x16x32_bf16 v[12:15], v[48:51], v[202:205], v[12:15]
	v_mfma_f32_16x16x32_bf16 v[8:11], v[56:59], v[202:205], v[8:11]
	v_mfma_f32_16x16x32_bf16 v[76:79], v[52:55], v[182:185], v[76:79]
	v_mfma_f32_16x16x32_bf16 v[72:75], v[60:63], v[182:185], v[72:75]
	v_mfma_f32_16x16x32_bf16 v[44:47], v[52:55], v[190:193], v[44:47]
	v_mfma_f32_16x16x32_bf16 v[40:43], v[60:63], v[190:193], v[40:43]
	v_mfma_f32_16x16x32_bf16 v[28:31], v[52:55], v[198:201], v[28:31]
	v_mfma_f32_16x16x32_bf16 v[24:27], v[60:63], v[198:201], v[24:27]
	v_mfma_f32_16x16x32_bf16 v[12:15], v[52:55], v[206:209], v[12:15]
	v_mfma_f32_16x16x32_bf16 v[8:11], v[60:63], v[206:209], v[8:11]
	v_mfma_f32_16x16x32_bf16 v[36:39], v[158:161], v[186:189], v[36:39]
	v_mfma_f32_16x16x32_bf16 v[32:35], v[170:173], v[186:189], v[32:35]
	v_mfma_f32_16x16x32_bf16 v[20:23], v[158:161], v[194:197], v[20:23]
	v_mfma_f32_16x16x32_bf16 v[16:19], v[170:173], v[194:197], v[16:19]
	v_mfma_f32_16x16x32_bf16 v[4:7], v[158:161], v[202:205], v[4:7]
	v_mfma_f32_16x16x32_bf16 v[0:3], v[170:173], v[202:205], v[0:3]
	v_mfma_f32_16x16x32_bf16 v[48:51], v[158:161], v[178:181], v[68:71]
	v_mfma_f32_16x16x32_bf16 v[52:55], v[170:173], v[178:181], v[64:67]
	v_mfma_f32_16x16x32_bf16 v[36:39], v[166:169], v[190:193], v[36:39]
	v_mfma_f32_16x16x32_bf16 v[32:35], v[174:177], v[190:193], v[32:35]
	v_mfma_f32_16x16x32_bf16 v[20:23], v[166:169], v[198:201], v[20:23]
	v_mfma_f32_16x16x32_bf16 v[16:19], v[174:177], v[198:201], v[16:19]
	v_mfma_f32_16x16x32_bf16 v[4:7], v[166:169], v[206:209], v[4:7]
	v_mfma_f32_16x16x32_bf16 v[0:3], v[174:177], v[206:209], v[0:3]
	v_mfma_f32_16x16x32_bf16 v[48:51], v[166:169], v[182:185], v[48:51]
	v_mfma_f32_16x16x32_bf16 v[52:55], v[174:177], v[182:185], v[52:55]
	s_setprio 0
	s_barrier
; #define PG8_STAGE(bufoff, gbase, voff) do { _Pragma("unroll") for (int _i = 0; _i < 2; ++_i) \
;         __builtin_amdgcn_global_load_lds((const unsigned*)((const char*)(gbase) + (voff)[_i]), (PG8_LAS unsigned*)(lds + (bufoff) + ldsw + _i * 8192), 16, 0, 0); } while (0)
; #define PG8_LDA(dst, b, h) do { _Pragma("unroll") for (int m = 0; m < 4; ++m) _Pragma("unroll") for (int k = 0; k < 2; ++k) dst[m][k] = *(const PG8_LAS bf16x8*)(lds + PG8_SA(b, h) + aoff + m * 2048 + k * 1024); } while (0)
; #define PG8_LDB(dst, b, h) do { _Pragma("unroll") for (int n = 0; n < 2; ++n) _Pragma("unroll") for (int k = 0; k < 2; ++k) dst[n][k] = *(const PG8_LAS bf16x8*)(lds + PG8_SB(b, h) + boff + n * 2048 + k * 1024); } while (0)
; #define PG8_MMA(ai, bj, At, Bt) do { __builtin_amdgcn_s_setprio(1); _Pragma("unroll") for (int m = 0; m < 4; ++m) _Pragma("unroll") for (int n = 0; n < 2; ++n) _Pragma("unroll") for (int k = 0; k < 2; ++k) \
;         acc[ai][bj][m][n] = __builtin_amdgcn_mfma_f32_16x16x32_bf16(Bt[n][k], At[m][k], acc[ai][bj][m][n], 0, 0, 0); __builtin_amdgcn_s_setprio(0); } while (0)
; #define PG8_WAIT_V(n) asm volatile("s_waitcnt vmcnt(" #n ")" ::: "memory")
; #define PG8_WAIT_L(n) asm volatile("s_waitcnt lgkmcnt(" #n ")" ::: "memory")
; #define PG8_BAR __builtin_amdgcn_s_barrier()
; #define PG8_SCHED __builtin_amdgcn_sched_barrier(0)
; template <class Epi, class Sched, bool ALIGN_EPI = false, bool SP2 = false>
; __device__ __forceinline__ void gemm_phase(PG8_LAS unsigned char* lds, const Gemm g, const Sched& S, const Epi& E, int tid_in) {
;     ...
;             PG8_LDB(B0, 1, 0); PG8_LDB(B1, 1, 1); PG8_SCHED; PG8_LDA(At, 1, 0); PG8_STAGE(PG8_SA(0, 1), a2 + hstep, voffA);
;             PG8_WAIT_V(8); PG8_WAIT_L(0); PG8_BAR; PG8_MMA(0, 0, At, B0); PG8_MMA(0, 1, At, B1); PG8_BAR; PG8_SCHED;
;             PG8_LDA(At, 1, 1); PG8_STAGE(PG8_SB(1, 0), b3, voffB); PG8_STAGE(PG8_SB(1, 1), b3 + hstep, voffB); PG8_STAGE(PG8_SA(1, 0), a3, voffA);
;             PG8_WAIT_V(8); PG8_WAIT_L(0); PG8_BAR; PG8_MMA(1, 0, At, B0); PG8_MMA(1, 1, At, B1); PG8_BAR; PG8_SCHED;
	s_add_i32 s33, 0, 0x18000
	s_add_i32 s34, 0, 0x1c000
	v_add_u32_e32 v68, s33, v164
	v_add_u32_e32 v174, s34, v164
	ds_read_b128 v[56:59], v68
	ds_read_b128 v[60:63], v68 offset:1024
	ds_read_b128 v[64:67], v68 offset:2048
	ds_read_b128 v[68:71], v68 offset:3072
	ds_read_b128 v[158:161], v174
	ds_read_b128 v[166:169], v174 offset:1024
	ds_read_b128 v[170:173], v174 offset:2048
	ds_read_b128 v[174:177], v174 offset:3072
	s_add_u32 s2, s24, 0x40000
	s_addc_u32 s3, s25, 0
	s_mov_b32 m0, s37
	ds_read_b128 v[178:181], v165 offset:32768
	ds_read_b128 v[182:185], v165 offset:33792
	ds_read_b128 v[186:189], v165 offset:34816
	ds_read_b128 v[190:193], v165 offset:35840
	ds_read_b128 v[194:197], v165 offset:36864
	ds_read_b128 v[198:201], v165 offset:37888
	ds_read_b128 v[202:205], v165 offset:38912
	ds_read_b128 v[206:209], v165 offset:39936
	global_load_lds_dwordx4 v152, s[2:3]
	s_mov_b32 m0, s38
	s_nop 0
	global_load_lds_dwordx4 v150, s[2:3]
	s_waitcnt vmcnt(8)
	s_waitcnt lgkmcnt(0)
	s_barrier
	s_setprio 1
	s_waitcnt lgkmcnt(0)
	v_mfma_f32_16x16x32_bf16 v[140:143], v[56:59], v[178:181], v[140:143]
	v_mfma_f32_16x16x32_bf16 v[136:139], v[64:67], v[178:181], v[136:139]
	v_mfma_f32_16x16x32_bf16 v[124:127], v[56:59], v[186:189], v[124:127]
	v_mfma_f32_16x16x32_bf16 v[120:123], v[64:67], v[186:189], v[120:123]
	v_mfma_f32_16x16x32_bf16 v[108:111], v[56:59], v[194:197], v[108:111]
	v_mfma_f32_16x16x32_bf16 v[104:107], v[64:67], v[194:197], v[104:107]
	v_mfma_f32_16x16x32_bf16 v[92:95], v[56:59], v[202:205], v[92:95]
	v_mfma_f32_16x16x32_bf16 v[88:91], v[64:67], v[202:205], v[88:91]
	v_mfma_f32_16x16x32_bf16 v[140:143], v[60:63], v[182:185], v[140:143]
	v_mfma_f32_16x16x32_bf16 v[136:139], v[68:71], v[182:185], v[136:139]
	v_mfma_f32_16x16x32_bf16 v[124:127], v[60:63], v[190:193], v[124:127]
	v_mfma_f32_16x16x32_bf16 v[120:123], v[68:71], v[190:193], v[120:123]
	v_mfma_f32_16x16x32_bf16 v[108:111], v[60:63], v[198:201], v[108:111]
	v_mfma_f32_16x16x32_bf16 v[104:107], v[68:71], v[198:201], v[104:107]
	v_mfma_f32_16x16x32_bf16 v[92:95], v[60:63], v[206:209], v[92:95]
	v_mfma_f32_16x16x32_bf16 v[88:91], v[68:71], v[206:209], v[88:91]
	v_mfma_f32_16x16x32_bf16 v[132:135], v[158:161], v[178:181], v[132:135]
	v_mfma_f32_16x16x32_bf16 v[128:131], v[170:173], v[178:181], v[128:131]
	v_mfma_f32_16x16x32_bf16 v[116:119], v[158:161], v[186:189], v[116:119]
	v_mfma_f32_16x16x32_bf16 v[112:115], v[170:173], v[186:189], v[112:115]
	v_mfma_f32_16x16x32_bf16 v[100:103], v[158:161], v[194:197], v[100:103]
	v_mfma_f32_16x16x32_bf16 v[96:99], v[170:173], v[194:197], v[96:99]
	v_mfma_f32_16x16x32_bf16 v[84:87], v[158:161], v[202:205], v[84:87]
	v_mfma_f32_16x16x32_bf16 v[80:83], v[170:173], v[202:205], v[80:83]
	v_mfma_f32_16x16x32_bf16 v[132:135], v[166:169], v[182:185], v[132:135]
	v_mfma_f32_16x16x32_bf16 v[128:131], v[174:177], v[182:185], v[128:131]
	v_mfma_f32_16x16x32_bf16 v[116:119], v[166:169], v[190:193], v[116:119]
	v_mfma_f32_16x16x32_bf16 v[112:115], v[174:177], v[190:193], v[112:115]
	v_mfma_f32_16x16x32_bf16 v[100:103], v[166:169], v[198:201], v[100:103]
	v_mfma_f32_16x16x32_bf16 v[96:99], v[174:177], v[198:201], v[96:99]
	v_mfma_f32_16x16x32_bf16 v[84:87], v[166:169], v[206:209], v[84:87]
	v_mfma_f32_16x16x32_bf16 v[80:83], v[174:177], v[206:209], v[80:83]
	s_setprio 0
	s_barrier
	s_add_i32 s2, s33, s35
	s_add_u32 s98, s22, 0x80
	s_addc_u32 s99, s23, 0
	s_mov_b32 m0, s2
	ds_read_b128 v[178:181], v165 offset:49152
	ds_read_b128 v[182:185], v165 offset:50176
	ds_read_b128 v[186:189], v165 offset:51200
	ds_read_b128 v[190:193], v165 offset:52224
	ds_read_b128 v[194:197], v165 offset:53248
	ds_read_b128 v[198:201], v165 offset:54272
	ds_read_b128 v[202:205], v165 offset:55296
	ds_read_b128 v[206:209], v165 offset:56320
	global_load_lds_dwordx4 v144, s[98:99]
	s_add_i32 m0, s2, 0x2000
	s_add_u32 s2, s22, 0x40080
	s_addc_u32 s3, s23, 0
	s_add_i32 s22, s34, s35
	global_load_lds_dwordx4 v148, s[98:99]
	s_mov_b32 m0, s22
	s_nop 0
	global_load_lds_dwordx4 v144, s[2:3]
	s_add_i32 m0, s22, 0x2000
	s_nop 0
	global_load_lds_dwordx4 v148, s[2:3]
	s_add_u32 s98, s24, 0x80
	s_addc_u32 s99, s25, 0
	s_mov_b32 m0, s41
	s_nop 0
	global_load_lds_dwordx4 v152, s[98:99]
	s_mov_b32 m0, s42
	s_nop 0
	global_load_lds_dwordx4 v150, s[98:99]
	s_waitcnt vmcnt(8)
	s_waitcnt lgkmcnt(0)
	s_barrier
	s_setprio 1
	s_waitcnt lgkmcnt(0)
	v_mfma_f32_16x16x32_bf16 v[76:79], v[56:59], v[178:181], v[76:79]
	v_mfma_f32_16x16x32_bf16 v[72:75], v[64:67], v[178:181], v[72:75]
	v_mfma_f32_16x16x32_bf16 v[44:47], v[56:59], v[186:189], v[44:47]
	v_mfma_f32_16x16x32_bf16 v[40:43], v[64:67], v[186:189], v[40:43]
	v_mfma_f32_16x16x32_bf16 v[28:31], v[56:59], v[194:197], v[28:31]
	v_mfma_f32_16x16x32_bf16 v[24:27], v[64:67], v[194:197], v[24:27]
	v_mfma_f32_16x16x32_bf16 v[12:15], v[56:59], v[202:205], v[12:15]
	v_mfma_f32_16x16x32_bf16 v[8:11], v[64:67], v[202:205], v[8:11]
	v_mfma_f32_16x16x32_bf16 v[76:79], v[60:63], v[182:185], v[76:79]
	v_mfma_f32_16x16x32_bf16 v[72:75], v[68:71], v[182:185], v[72:75]
	v_mfma_f32_16x16x32_bf16 v[44:47], v[60:63], v[190:193], v[44:47]
	v_mfma_f32_16x16x32_bf16 v[40:43], v[68:71], v[190:193], v[40:43]
	v_mfma_f32_16x16x32_bf16 v[28:31], v[60:63], v[198:201], v[28:31]
	v_mfma_f32_16x16x32_bf16 v[24:27], v[68:71], v[198:201], v[24:27]
	v_mfma_f32_16x16x32_bf16 v[12:15], v[60:63], v[206:209], v[12:15]
	v_mfma_f32_16x16x32_bf16 v[8:11], v[68:71], v[206:209], v[8:11]
	v_mfma_f32_16x16x32_bf16 v[48:51], v[158:161], v[178:181], v[48:51]
	v_mfma_f32_16x16x32_bf16 v[68:71], v[166:169], v[182:185], v[48:51]
	v_mfma_f32_16x16x32_bf16 v[48:51], v[170:173], v[178:181], v[52:55]
	v_mfma_f32_16x16x32_bf16 v[36:39], v[158:161], v[186:189], v[36:39]
	v_mfma_f32_16x16x32_bf16 v[32:35], v[170:173], v[186:189], v[32:35]
	v_mfma_f32_16x16x32_bf16 v[20:23], v[158:161], v[194:197], v[20:23]
	v_mfma_f32_16x16x32_bf16 v[16:19], v[170:173], v[194:197], v[16:19]
	v_mfma_f32_16x16x32_bf16 v[4:7], v[158:161], v[202:205], v[4:7]
	v_mfma_f32_16x16x32_bf16 v[0:3], v[170:173], v[202:205], v[0:3]
	v_mfma_f32_16x16x32_bf16 v[64:67], v[174:177], v[182:185], v[48:51]
	v_mfma_f32_16x16x32_bf16 v[36:39], v[166:169], v[190:193], v[36:39]
	v_mfma_f32_16x16x32_bf16 v[32:35], v[174:177], v[190:193], v[32:35]
	v_mfma_f32_16x16x32_bf16 v[20:23], v[166:169], v[198:201], v[20:23]
	v_mfma_f32_16x16x32_bf16 v[16:19], v[174:177], v[198:201], v[16:19]
	v_mfma_f32_16x16x32_bf16 v[4:7], v[166:169], v[206:209], v[4:7]
	v_mfma_f32_16x16x32_bf16 v[0:3], v[174:177], v[206:209], v[0:3]
	s_setprio 0
	s_barrier
	s_add_i32 s49, s49, 2
	s_add_u32 s20, s20, 0x100
	s_addc_u32 s21, s21, 0
	s_add_u32 s47, s47, 0x100
	s_addc_u32 s48, s48, 0
	s_cmp_gt_u32 s49, 13
	s_cbranch_scc0 .LBB0_351
	s_and_b64 vcc, exec, s[6:7]
	s_cbranch_vccz .LBB0_354
	s_barrier
